# v8 + relaxed vmcnt(20) in peeled first super-phases of FFN-out/out-proj units + ml_phase_a unit-top wait vmcnt(4) leaves state-tile stores in flight
# speedup vs baseline: 1.0093x; 1.0024x over previous
; #define PG8_STAGE(bufoff, gbase, voff) do { _Pragma("unroll") for (int _i = 0; _i < 2; ++_i) \
;         __builtin_amdgcn_global_load_lds((const unsigned*)((const char*)(gbase) + (voff)[_i]), (PG8_LAS unsigned*)(lds + (bufoff) + ldsw + _i * 8192), 16, 0, 0); } while (0)
; #define PG8_WAIT_V(n) asm volatile("s_waitcnt vmcnt(" #n ")" ::: "memory")
; #define PG8_BAR __builtin_amdgcn_s_barrier()
; template <class Epi, class Sched, bool ALIGN_EPI = false, bool SP2 = false>
; __device__ __forceinline__ void gemm_phase(PG8_LAS unsigned char* lds, const Gemm g, const Sched& S, const Epi& E) {
;     ...
;     const int aoff = lds_byte(wr * 64 + fr, fq * 8), boff = lds_byte(wc * 32 + fr, fq * 8);
;     ...
;     Unit cur, nxt; int ui = 0;
;     if (!S.next(0, cur)) return;
;     f32x4 acc[2][2][4][2];
; #pragma unroll
;     for (int a = 0; a < 2; ++a)
; #pragma unroll
;         for (int b = 0; b < 2; ++b)
; #pragma unroll
;             for (int m = 0; m < 4; ++m)
; #pragma unroll
;                 for (int n = 0; n < 2; ++n) acc[a][b][m][n] = (f32x4){0.f, 0.f, 0.f, 0.f};
;     bf16x8 At[4][2], B0[2][2], B1[2][2];
;     const char* cA = (const char*)g.A + (size_t)cur.pm * tstep; const char* cB = (const char*)g.Bt + (size_t)cur.pn * tstep;
;     S.a_ready(cur);
;     if constexpr (SP2) {
;         PG8_STAGE(PG8_SB(0, 0), cB, voffB); PG8_STAGE(PG8_SB(0, 1), cB + hstep, voffB); PG8_STAGE(PG8_SA(0, 0), cA, voffA); PG8_STAGE(PG8_SA(0, 1), cA + hstep, voffA);
;         if (wr == 1) PG8_BAR;
;         PG8_WAIT_V(2); PG8_BAR;
;         PG8_STAGE(PG8_SB(1, 0), cB + kstep, voffB); PG8_STAGE(PG8_SA(1, 0), cA + kstep, voffA); PG8_STAGE(PG8_SB(1, 1), cB + hstep + kstep, voffB);
;         PG8_WAIT_V(6); PG8_BAR;
.LBB0_422:
	s_mul_i32 s86, s54, 0xc00
	s_lshl_b64 s[8:9], s[86:87], 2
	s_add_u32 s7, s7, s8
	s_addc_u32 s8, s10, s9
	v_lshrrev_b32_e32 v18, 1, v12
	s_add_u32 s29, s7, 0x2000
	v_and_b32_e32 v18, 24, v18
	v_readlane_b32 s16, v254, 19
	s_addc_u32 s30, s8, 0
	v_and_b32_e32 v13, 15, v12
	v_lshlrev_b32_e32 v19, 1, v18
	v_lshlrev_b32_e32 v12, 2, v12
	s_lshl_b32 s5, s5, 5
	v_mov_b32_e32 v159, v1
	v_readlane_b32 s17, v254, 20
	v_lshl_or_b32 v200, s6, 6, v13
	v_lshl_or_b32 v13, v13, 6, v19
	s_lshl_b32 s6, s6, 13
	v_and_b32_e32 v12, 32, v12
	s_and_b32 s5, s5, 0x60
	s_add_i32 m0, s25, 0x18000
	v_lshl_add_u64 v[2:3], v[2:3], 0, s[38:39]
	v_lshl_add_u64 v[14:15], s[16:17], 0, v[158:159]
	v_mov_b32_e32 v157, v1
	v_bitop3_b32 v19, v13, s6, v12 bitop3:0xde
	s_lshl_b32 s6, s5, 7
	s_waitcnt vmcnt(2)
	s_barrier
	global_load_lds_dwordx4 v[2:3], off
	v_lshl_add_u64 v[2:3], v[4:5], 0, s[38:39]
	s_add_i32 m0, s25, 0x1a000
	s_add_i32 s31, s25, 0x8000
	s_add_i32 s33, s25, 0xa000
	v_lshl_add_u64 v[16:17], s[16:17], 0, v[156:157]
	v_bitop3_b32 v201, v13, s6, v12 bitop3:0xde
	global_load_lds_dwordx4 v[2:3], off
	v_lshl_add_u64 v[2:3], v[14:15], 0, s[38:39]
	s_mov_b32 m0, s31
	s_add_u32 s6, s18, 0x100080
	global_load_lds_dwordx4 v[2:3], off
	v_lshl_add_u64 v[2:3], v[16:17], 0, s[38:39]
	s_mov_b32 m0, s33
	s_addc_u32 s7, s19, 0
	global_load_lds_dwordx4 v[2:3], off
	s_add_i32 m0, s25, 0x1c000
	v_lshl_add_u64 v[2:3], s[6:7], 0, v[0:1]
	global_load_lds_dwordx4 v[2:3], off
	v_lshl_add_u64 v[2:3], s[6:7], 0, v[154:155]
	s_add_i32 m0, s25, 0x1e000
	s_cmpk_lt_u32 s4, 0x100
	global_load_lds_dwordx4 v[2:3], off
	v_lshlrev_b32_e32 v2, 16, v10
	v_and_b32_e32 v2, 0xfffe0000, v2
	v_lshl_add_u32 v2, v9, 13, v2
	v_and_b32_e32 v3, 1, v10
	v_lshl_or_b32 v2, v3, 6, v2
	v_lshl_add_u32 v160, v11, 1, v2
	v_lshlrev_b32_e32 v2, 16, v6
	v_and_b32_e32 v2, 0xfffe0000, v2
	s_waitcnt vmcnt(6)
	v_lshl_add_u32 v2, v7, 13, v2
	v_and_b32_e32 v3, 1, v6
	v_or_b32_e32 v202, s5, v18
	v_lshl_or_b32 v2, v3, 6, v2
	v_readlane_b32 s4, v254, 16
	s_cselect_b64 s[6:7], -1, 0
	v_mov_b32_e32 v161, v1
	v_lshl_add_u32 v162, v8, 1, v2
	v_mov_b32_e32 v163, v1
	s_mov_b32 s48, 0
	v_add_u32_e32 v203, 0, v19
	v_readlane_b32 s50, v254, 7
	s_mov_b32 s49, s4
	s_barrier
	v_readlane_b32 s5, v254, 17
	s_waitcnt vmcnt(0)
	s_branch .LBB0_425

; #define PG8_STAGE(bufoff, gbase, voff) do { _Pragma("unroll") for (int _i = 0; _i < 2; ++_i) \
;         __builtin_amdgcn_global_load_lds((const unsigned*)((const char*)(gbase) + (voff)[_i]), (PG8_LAS unsigned*)(lds + (bufoff) + ldsw + _i * 8192), 16, 0, 0); } while (0)
; #define PG8_LDA(dst, b, h) do { _Pragma("unroll") for (int m = 0; m < 4; ++m) _Pragma("unroll") for (int k = 0; k < 2; ++k) dst[m][k] = *(const PG8_LAS bf16x8*)(lds + PG8_SA(b, h) + aoff + m * 2048 + k * 1024); } while (0)
; #define PG8_LDB(dst, b, h) do { _Pragma("unroll") for (int n = 0; n < 2; ++n) _Pragma("unroll") for (int k = 0; k < 2; ++k) dst[n][k] = *(const PG8_LAS bf16x8*)(lds + PG8_SB(b, h) + boff + n * 2048 + k * 1024); } while (0)
; #define PG8_MMA(ai, bj, At, Bt) do { __builtin_amdgcn_s_setprio(1); _Pragma("unroll") for (int m = 0; m < 4; ++m) _Pragma("unroll") for (int n = 0; n < 2; ++n) _Pragma("unroll") for (int k = 0; k < 2; ++k) \
;         acc[ai][bj][m][n] = __builtin_amdgcn_mfma_f32_16x16x32_bf16(Bt[n][k], At[m][k], acc[ai][bj][m][n], 0, 0, 0); __builtin_amdgcn_s_setprio(0); } while (0)
; #define PG8_BAR __builtin_amdgcn_s_barrier()
; template <class Epi, class Sched, bool ALIGN_EPI = false, bool SP2 = false>
; __device__ __forceinline__ void gemm_phase(PG8_LAS unsigned char* lds, const Gemm g, const Sched& S, const Epi& E) {
;     ...
;         const bool has_next = S.next(ui + 1, nxt);
;         const char* nA = has_next ? (const char*)g.A + (size_t)nxt.pm * tstep : cA; const char* nB = has_next ? (const char*)g.Bt + (size_t)nxt.pn * tstep : cB;
;         for (int t = 0; t < nt; t += 2) {
;             const bool last = (t == nt - 2);
;             const char* a1 = cA + (size_t)(t + 1) * kstep;
;             const char* a2 = last ? nA : cA + (size_t)(t + 2) * kstep; const char* b2 = last ? nB : cB + (size_t)(t + 2) * kstep;
;             const char* a3 = a2 + kstep; const char* b3 = b2 + kstep;
;             if (last && has_next) S.a_ready(nxt);
;             if constexpr (SP2) {
;             PG8_LDB(B0, 0, 0); PG8_LDB(B1, 0, 1); PG8_SCHED; PG8_LDA(At, 0, 0); PG8_STAGE(PG8_SA(1, 1), a1 + hstep, voffA);
;             PG8_WAIT_V(8); PG8_WAIT_L(0); PG8_BAR; PG8_MMA(0, 0, At, B0); PG8_MMA(0, 1, At, B1); PG8_BAR; PG8_SCHED;
;             PG8_LDA(At, 0, 1); PG8_STAGE(PG8_SB(0, 0), b2, voffB); PG8_STAGE(PG8_SB(0, 1), b2 + hstep, voffB); PG8_STAGE(PG8_SA(0, 0), a2, voffA);
.LBB0_431:
	s_ashr_i32 s11, s10, 31
	s_lshl_b64 s[12:13], s[10:11], 21
	s_add_u32 s12, s92, s12
	s_addc_u32 s13, s93, s13
	s_and_b64 s[14:15], s[4:5], exec
	s_cselect_b32 s11, s13, s17
	s_cselect_b32 s51, s12, s16
	s_ashr_i32 s9, s8, 31
	s_lshl_b64 s[14:15], s[8:9], 21
	s_add_u32 s14, s22, s14
	s_addc_u32 s15, s23, s15
	s_and_b64 s[20:21], s[4:5], exec
	s_cselect_b32 s9, s15, s19
	s_cselect_b32 s52, s14, s18
	s_add_u32 s16, s16, 0x100080
	s_addc_u32 s17, s17, 0
	s_add_u32 s53, s18, 0x100
	s_addc_u32 s54, s19, 0
	s_mov_b32 s55, -2
	s_add_u32 s18, s16, 0xfff00080
	s_addc_u32 s19, s17, -1
	s_add_i32 s56, 0, 0x10000
	s_cmp_eq_u32 s55, 60
	s_cselect_b32 s21, s11, s19
	s_cselect_b32 s20, s51, s18
	s_cselect_b32 s19, s9, s54
	s_cselect_b32 s18, s52, s53
	s_add_i32 s58, 0, 0x14000
	v_add_u32_e32 v142, s56, v201
	v_add_u32_e32 v146, s58, v201
	ds_read_b128 v[130:133], v142
	ds_read_b128 v[134:137], v142 offset:1024
	ds_read_b128 v[138:141], v142 offset:2048
	ds_read_b128 v[142:145], v142 offset:3072
	ds_read_b128 v[164:167], v146
	ds_read_b128 v[168:171], v146 offset:1024
	ds_read_b128 v[172:175], v146 offset:2048
	ds_read_b128 v[176:179], v146 offset:3072
	v_lshl_add_u64 v[146:147], s[16:17], 0, v[160:161]
	s_add_i32 m0, s25, 0xc000
	ds_read_b128 v[204:207], v203
	ds_read_b128 v[208:211], v203 offset:1024
	ds_read_b128 v[212:215], v203 offset:2048
	ds_read_b128 v[216:219], v203 offset:3072
	ds_read_b128 v[220:223], v203 offset:4096
	ds_read_b128 v[224:227], v203 offset:5120
	ds_read_b128 v[228:231], v203 offset:6144
	ds_read_b128 v[232:235], v203 offset:7168
	global_load_lds_dwordx4 v[146:147], off
	v_lshl_add_u64 v[146:147], s[16:17], 0, v[162:163]
	s_add_i32 m0, s25, 0xe000
	s_nop 0
	global_load_lds_dwordx4 v[146:147], off
	s_waitcnt vmcnt(20)
	s_waitcnt lgkmcnt(0)
	s_barrier
	s_setprio 1
	s_waitcnt lgkmcnt(0)
	v_mfma_f32_16x16x32_bf16 v[126:129], v[130:133], v[204:207], 0
	v_mfma_f32_16x16x32_bf16 v[122:125], v[138:141], v[204:207], 0
	v_mfma_f32_16x16x32_bf16 v[118:121], v[130:133], v[212:215], 0
	v_mfma_f32_16x16x32_bf16 v[114:117], v[138:141], v[212:215], 0
	v_mfma_f32_16x16x32_bf16 v[110:113], v[130:133], v[220:223], 0
	v_mfma_f32_16x16x32_bf16 v[106:109], v[138:141], v[220:223], 0
	v_mfma_f32_16x16x32_bf16 v[102:105], v[130:133], v[228:231], 0
	v_mfma_f32_16x16x32_bf16 v[98:101], v[138:141], v[228:231], 0
	v_mfma_f32_16x16x32_bf16 v[126:129], v[134:137], v[208:211], v[126:129]
	v_mfma_f32_16x16x32_bf16 v[122:125], v[142:145], v[208:211], v[122:125]
	v_mfma_f32_16x16x32_bf16 v[118:121], v[134:137], v[216:219], v[118:121]
	v_mfma_f32_16x16x32_bf16 v[114:117], v[142:145], v[216:219], v[114:117]
	v_mfma_f32_16x16x32_bf16 v[110:113], v[134:137], v[224:227], v[110:113]
	v_mfma_f32_16x16x32_bf16 v[106:109], v[142:145], v[224:227], v[106:109]
	v_mfma_f32_16x16x32_bf16 v[102:105], v[134:137], v[232:235], v[102:105]
	v_mfma_f32_16x16x32_bf16 v[98:101], v[142:145], v[232:235], v[98:101]
	s_setprio 0
	s_setprio 1
	v_mfma_f32_16x16x32_bf16 v[62:65], v[164:167], v[204:207], 0
	v_mfma_f32_16x16x32_bf16 v[58:61], v[172:175], v[204:207], 0
	v_mfma_f32_16x16x32_bf16 v[54:57], v[164:167], v[212:215], 0
	v_mfma_f32_16x16x32_bf16 v[50:53], v[172:175], v[212:215], 0
	v_mfma_f32_16x16x32_bf16 v[46:49], v[164:167], v[220:223], 0
	v_mfma_f32_16x16x32_bf16 v[42:45], v[172:175], v[220:223], 0
	v_mfma_f32_16x16x32_bf16 v[38:41], v[164:167], v[228:231], 0
	v_mfma_f32_16x16x32_bf16 v[34:37], v[172:175], v[228:231], 0
	v_mfma_f32_16x16x32_bf16 v[62:65], v[168:171], v[208:211], v[62:65]
	v_mfma_f32_16x16x32_bf16 v[58:61], v[176:179], v[208:211], v[58:61]
	v_mfma_f32_16x16x32_bf16 v[54:57], v[168:171], v[216:219], v[54:57]
	v_mfma_f32_16x16x32_bf16 v[50:53], v[176:179], v[216:219], v[50:53]
	v_mfma_f32_16x16x32_bf16 v[46:49], v[168:171], v[224:227], v[46:49]
	v_mfma_f32_16x16x32_bf16 v[42:45], v[176:179], v[224:227], v[42:45]
	v_mfma_f32_16x16x32_bf16 v[38:41], v[168:171], v[232:235], v[38:41]
	v_mfma_f32_16x16x32_bf16 v[34:37], v[176:179], v[232:235], v[34:37]
	s_setprio 0
	s_barrier
	s_add_i32 s56, s56, s24
	v_lshl_add_u64 v[146:147], s[18:19], 0, v[0:1]
	s_mov_b32 m0, s56
	ds_read_b128 v[204:207], v203 offset:16384
	ds_read_b128 v[208:211], v203 offset:17408
	ds_read_b128 v[212:215], v203 offset:18432
	ds_read_b128 v[216:219], v203 offset:19456
	ds_read_b128 v[220:223], v203 offset:20480
	ds_read_b128 v[224:227], v203 offset:21504
	ds_read_b128 v[228:231], v203 offset:22528
	ds_read_b128 v[232:235], v203 offset:23552
	global_load_lds_dwordx4 v[146:147], off
	s_add_i32 m0, s56, 0x2000
	s_add_u32 s56, s18, 0x100000
	v_lshl_add_u64 v[148:149], s[18:19], 0, v[154:155]
	s_addc_u32 s57, s19, 0
	s_add_i32 s58, s58, s24
	global_load_lds_dwordx4 v[148:149], off
	v_lshl_add_u64 v[180:181], s[56:57], 0, v[0:1]
	s_mov_b32 m0, s58
	v_lshl_add_u64 v[236:237], s[20:21], 0, v[156:157]
	global_load_lds_dwordx4 v[180:181], off
	v_lshl_add_u64 v[180:181], s[56:57], 0, v[154:155]
	s_add_i32 m0, s58, 0x2000
	s_nop 0
	global_load_lds_dwordx4 v[180:181], off
	v_lshl_add_u64 v[180:181], s[20:21], 0, v[158:159]
	s_mov_b32 m0, s25
	s_nop 0
	global_load_lds_dwordx4 v[180:181], off
	s_mov_b32 m0, s26
	s_nop 0
	global_load_lds_dwordx4 v[236:237], off
	s_waitcnt vmcnt(20)
	s_waitcnt lgkmcnt(0)
	s_barrier
; #define PG8_STAGE(bufoff, gbase, voff) do { _Pragma("unroll") for (int _i = 0; _i < 2; ++_i) \
;         __builtin_amdgcn_global_load_lds((const unsigned*)((const char*)(gbase) + (voff)[_i]), (PG8_LAS unsigned*)(lds + (bufoff) + ldsw + _i * 8192), 16, 0, 0); } while (0)
; #define PG8_LDA(dst, b, h) do { _Pragma("unroll") for (int m = 0; m < 4; ++m) _Pragma("unroll") for (int k = 0; k < 2; ++k) dst[m][k] = *(const PG8_LAS bf16x8*)(lds + PG8_SA(b, h) + aoff + m * 2048 + k * 1024); } while (0)
; #define PG8_LDB(dst, b, h) do { _Pragma("unroll") for (int n = 0; n < 2; ++n) _Pragma("unroll") for (int k = 0; k < 2; ++k) dst[n][k] = *(const PG8_LAS bf16x8*)(lds + PG8_SB(b, h) + boff + n * 2048 + k * 1024); } while (0)
; #define PG8_MMA(ai, bj, At, Bt) do { __builtin_amdgcn_s_setprio(1); _Pragma("unroll") for (int m = 0; m < 4; ++m) _Pragma("unroll") for (int n = 0; n < 2; ++n) _Pragma("unroll") for (int k = 0; k < 2; ++k) \
;         acc[ai][bj][m][n] = __builtin_amdgcn_mfma_f32_16x16x32_bf16(Bt[n][k], At[m][k], acc[ai][bj][m][n], 0, 0, 0); __builtin_amdgcn_s_setprio(0); } while (0)
; #define PG8_WAIT_V(n) asm volatile("s_waitcnt vmcnt(" #n ")" ::: "memory")
; #define PG8_WAIT_L(n) asm volatile("s_waitcnt lgkmcnt(" #n ")" ::: "memory")
; #define PG8_BAR __builtin_amdgcn_s_barrier()
; #define PG8_SCHED __builtin_amdgcn_sched_barrier(0)
; template <class Epi, class Sched, bool ALIGN_EPI = false, bool SP2 = false>
; __device__ __forceinline__ void gemm_phase(PG8_LAS unsigned char* lds, const Gemm g, const Sched& S, const Epi& E) {
;     ...
;             PG8_WAIT_V(8); PG8_WAIT_L(0); PG8_BAR; PG8_MMA(1, 0, At, B0); PG8_MMA(1, 1, At, B1); PG8_BAR; PG8_SCHED;
;             PG8_LDB(B0, 1, 0); PG8_LDB(B1, 1, 1); PG8_SCHED; PG8_LDA(At, 1, 0); PG8_STAGE(PG8_SA(0, 1), a2 + hstep, voffA);
;             PG8_WAIT_V(8); PG8_WAIT_L(0); PG8_BAR; PG8_MMA(0, 0, At, B0); PG8_MMA(0, 1, At, B1); PG8_BAR; PG8_SCHED;
;             PG8_LDA(At, 1, 1); PG8_STAGE(PG8_SB(1, 0), b3, voffB); PG8_STAGE(PG8_SB(1, 1), b3 + hstep, voffB); PG8_STAGE(PG8_SA(1, 0), a3, voffA);
	s_setprio 1
	s_waitcnt lgkmcnt(0)
	v_mfma_f32_16x16x32_bf16 v[94:97], v[130:133], v[204:207], 0
	v_mfma_f32_16x16x32_bf16 v[90:93], v[138:141], v[204:207], 0
	v_mfma_f32_16x16x32_bf16 v[86:89], v[130:133], v[212:215], 0
	v_mfma_f32_16x16x32_bf16 v[82:85], v[138:141], v[212:215], 0
	v_mfma_f32_16x16x32_bf16 v[78:81], v[130:133], v[220:223], 0
	v_mfma_f32_16x16x32_bf16 v[74:77], v[138:141], v[220:223], 0
	v_mfma_f32_16x16x32_bf16 v[70:73], v[130:133], v[228:231], 0
	v_mfma_f32_16x16x32_bf16 v[66:69], v[138:141], v[228:231], 0
	v_mfma_f32_16x16x32_bf16 v[94:97], v[134:137], v[208:211], v[94:97]
	v_mfma_f32_16x16x32_bf16 v[90:93], v[142:145], v[208:211], v[90:93]
	v_mfma_f32_16x16x32_bf16 v[86:89], v[134:137], v[216:219], v[86:89]
	v_mfma_f32_16x16x32_bf16 v[82:85], v[142:145], v[216:219], v[82:85]
	v_mfma_f32_16x16x32_bf16 v[78:81], v[134:137], v[224:227], v[78:81]
	v_mfma_f32_16x16x32_bf16 v[74:77], v[142:145], v[224:227], v[74:77]
	v_mfma_f32_16x16x32_bf16 v[70:73], v[134:137], v[232:235], v[70:73]
	v_mfma_f32_16x16x32_bf16 v[66:69], v[142:145], v[232:235], v[66:69]
	s_setprio 0
	s_setprio 1
	v_mfma_f32_16x16x32_bf16 v[30:33], v[164:167], v[204:207], 0
	v_mfma_f32_16x16x32_bf16 v[26:29], v[172:175], v[204:207], 0
	v_mfma_f32_16x16x32_bf16 v[22:25], v[164:167], v[212:215], 0
	v_mfma_f32_16x16x32_bf16 v[18:21], v[172:175], v[212:215], 0
	v_mfma_f32_16x16x32_bf16 v[14:17], v[164:167], v[220:223], 0
	v_mfma_f32_16x16x32_bf16 v[10:13], v[172:175], v[220:223], 0
	v_mfma_f32_16x16x32_bf16 v[6:9], v[164:167], v[228:231], 0
	v_mfma_f32_16x16x32_bf16 v[2:5], v[172:175], v[228:231], 0
	v_mfma_f32_16x16x32_bf16 v[30:33], v[168:171], v[208:211], v[30:33]
	v_mfma_f32_16x16x32_bf16 v[26:29], v[176:179], v[208:211], v[26:29]
	v_mfma_f32_16x16x32_bf16 v[22:25], v[168:171], v[216:219], v[22:25]
	v_mfma_f32_16x16x32_bf16 v[18:21], v[176:179], v[216:219], v[18:21]
	v_mfma_f32_16x16x32_bf16 v[14:17], v[168:171], v[224:227], v[14:17]
	v_mfma_f32_16x16x32_bf16 v[10:13], v[176:179], v[224:227], v[10:13]
	v_mfma_f32_16x16x32_bf16 v[6:9], v[168:171], v[232:235], v[6:9]
	v_mfma_f32_16x16x32_bf16 v[2:5], v[176:179], v[232:235], v[2:5]
	s_setprio 0
	s_barrier
	s_add_i32 s56, 0, 0x18000
	s_add_i32 s57, 0, 0x1c000
	v_add_u32_e32 v142, s56, v201
	v_add_u32_e32 v176, s57, v201
	ds_read_b128 v[130:133], v142
	ds_read_b128 v[134:137], v142 offset:1024
	ds_read_b128 v[138:141], v142 offset:2048
	ds_read_b128 v[142:145], v142 offset:3072
	ds_read_b128 v[164:167], v176
	ds_read_b128 v[168:171], v176 offset:1024
	ds_read_b128 v[172:175], v176 offset:2048
	ds_read_b128 v[176:179], v176 offset:3072
	s_add_u32 s20, s20, 0x100000
	s_addc_u32 s21, s21, 0
	s_mov_b32 m0, s27
	v_lshl_add_u64 v[238:239], s[20:21], 0, v[158:159]
	ds_read_b128 v[204:207], v203 offset:32768
	ds_read_b128 v[208:211], v203 offset:33792
	ds_read_b128 v[212:215], v203 offset:34816
	ds_read_b128 v[216:219], v203 offset:35840
	ds_read_b128 v[220:223], v203 offset:36864
	ds_read_b128 v[224:227], v203 offset:37888
	ds_read_b128 v[228:231], v203 offset:38912
	ds_read_b128 v[232:235], v203 offset:39936
	global_load_lds_dwordx4 v[238:239], off
	v_lshl_add_u64 v[238:239], s[20:21], 0, v[156:157]
	s_mov_b32 m0, s28
	s_nop 0
	global_load_lds_dwordx4 v[238:239], off
	s_waitcnt vmcnt(8)
	s_waitcnt lgkmcnt(0)
	s_barrier
	s_setprio 1
	s_waitcnt lgkmcnt(0)
	v_mfma_f32_16x16x32_bf16 v[126:129], v[130:133], v[204:207], v[126:129]
	v_mfma_f32_16x16x32_bf16 v[122:125], v[138:141], v[204:207], v[122:125]
	v_mfma_f32_16x16x32_bf16 v[118:121], v[130:133], v[212:215], v[118:121]
	v_mfma_f32_16x16x32_bf16 v[114:117], v[138:141], v[212:215], v[114:117]
	v_mfma_f32_16x16x32_bf16 v[110:113], v[130:133], v[220:223], v[110:113]
	v_mfma_f32_16x16x32_bf16 v[106:109], v[138:141], v[220:223], v[106:109]
	v_mfma_f32_16x16x32_bf16 v[102:105], v[130:133], v[228:231], v[102:105]
	v_mfma_f32_16x16x32_bf16 v[98:101], v[138:141], v[228:231], v[98:101]
	v_mfma_f32_16x16x32_bf16 v[126:129], v[134:137], v[208:211], v[126:129]
	v_mfma_f32_16x16x32_bf16 v[122:125], v[142:145], v[208:211], v[122:125]
	v_mfma_f32_16x16x32_bf16 v[118:121], v[134:137], v[216:219], v[118:121]
	v_mfma_f32_16x16x32_bf16 v[114:117], v[142:145], v[216:219], v[114:117]
	v_mfma_f32_16x16x32_bf16 v[110:113], v[134:137], v[224:227], v[110:113]
	v_mfma_f32_16x16x32_bf16 v[106:109], v[142:145], v[224:227], v[106:109]
	v_mfma_f32_16x16x32_bf16 v[102:105], v[134:137], v[232:235], v[102:105]
	v_mfma_f32_16x16x32_bf16 v[98:101], v[142:145], v[232:235], v[98:101]
	s_setprio 0
	s_setprio 1
	v_mfma_f32_16x16x32_bf16 v[62:65], v[164:167], v[204:207], v[62:65]
	v_mfma_f32_16x16x32_bf16 v[58:61], v[172:175], v[204:207], v[58:61]
	v_mfma_f32_16x16x32_bf16 v[54:57], v[164:167], v[212:215], v[54:57]
	v_mfma_f32_16x16x32_bf16 v[50:53], v[172:175], v[212:215], v[50:53]
	v_mfma_f32_16x16x32_bf16 v[46:49], v[164:167], v[220:223], v[46:49]
	v_mfma_f32_16x16x32_bf16 v[42:45], v[172:175], v[220:223], v[42:45]
	v_mfma_f32_16x16x32_bf16 v[38:41], v[164:167], v[228:231], v[38:41]
	v_mfma_f32_16x16x32_bf16 v[34:37], v[172:175], v[228:231], v[34:37]
	v_mfma_f32_16x16x32_bf16 v[62:65], v[168:171], v[208:211], v[62:65]
	v_mfma_f32_16x16x32_bf16 v[58:61], v[176:179], v[208:211], v[58:61]
	v_mfma_f32_16x16x32_bf16 v[54:57], v[168:171], v[216:219], v[54:57]
	v_mfma_f32_16x16x32_bf16 v[50:53], v[176:179], v[216:219], v[50:53]
	v_mfma_f32_16x16x32_bf16 v[46:49], v[168:171], v[224:227], v[46:49]
	v_mfma_f32_16x16x32_bf16 v[42:45], v[176:179], v[224:227], v[42:45]
	v_mfma_f32_16x16x32_bf16 v[38:41], v[168:171], v[232:235], v[38:41]
	v_mfma_f32_16x16x32_bf16 v[34:37], v[176:179], v[232:235], v[34:37]
	s_setprio 0
	s_barrier
; #define PG8_STAGE(bufoff, gbase, voff) do { _Pragma("unroll") for (int _i = 0; _i < 2; ++_i) \
;         __builtin_amdgcn_global_load_lds((const unsigned*)((const char*)(gbase) + (voff)[_i]), (PG8_LAS unsigned*)(lds + (bufoff) + ldsw + _i * 8192), 16, 0, 0); } while (0)
; #define PG8_LDA(dst, b, h) do { _Pragma("unroll") for (int m = 0; m < 4; ++m) _Pragma("unroll") for (int k = 0; k < 2; ++k) dst[m][k] = *(const PG8_LAS bf16x8*)(lds + PG8_SA(b, h) + aoff + m * 2048 + k * 1024); } while (0)
; #define PG8_MMA(ai, bj, At, Bt) do { __builtin_amdgcn_s_setprio(1); _Pragma("unroll") for (int m = 0; m < 4; ++m) _Pragma("unroll") for (int n = 0; n < 2; ++n) _Pragma("unroll") for (int k = 0; k < 2; ++k) \
;         acc[ai][bj][m][n] = __builtin_amdgcn_mfma_f32_16x16x32_bf16(Bt[n][k], At[m][k], acc[ai][bj][m][n], 0, 0, 0); __builtin_amdgcn_s_setprio(0); } while (0)
; #define PG8_WAIT_V(n) asm volatile("s_waitcnt vmcnt(" #n ")" ::: "memory")
; #define PG8_WAIT_L(n) asm volatile("s_waitcnt lgkmcnt(" #n ")" ::: "memory")
; #define PG8_BAR __builtin_amdgcn_s_barrier()
; #define PG8_SCHED __builtin_amdgcn_sched_barrier(0)
; template <class Epi, class Sched, bool ALIGN_EPI = false, bool SP2 = false>
; __device__ __forceinline__ void gemm_phase(PG8_LAS unsigned char* lds, const Gemm g, const Sched& S, const Epi& E) {
;     ...
;         for (int t = 0; t < nt; t += 2) {
;             const bool last = (t == nt - 2);
;             const char* a1 = cA + (size_t)(t + 1) * kstep;
;             const char* a2 = last ? nA : cA + (size_t)(t + 2) * kstep; const char* b2 = last ? nB : cB + (size_t)(t + 2) * kstep;
;             const char* a3 = a2 + kstep; const char* b3 = b2 + kstep;
;     ...
;             PG8_LDA(At, 1, 1); PG8_STAGE(PG8_SB(1, 0), b3, voffB); PG8_STAGE(PG8_SB(1, 1), b3 + hstep, voffB); PG8_STAGE(PG8_SA(1, 0), a3, voffA);
;             PG8_WAIT_V(8); PG8_WAIT_L(0); PG8_BAR; PG8_MMA(1, 0, At, B0); PG8_MMA(1, 1, At, B1); PG8_BAR; PG8_SCHED;
	s_add_i32 s20, s56, s24
	v_lshl_add_u64 v[146:147], v[146:147], 0, s[38:39]
	s_mov_b32 m0, s20
	ds_read_b128 v[204:207], v203 offset:49152
	ds_read_b128 v[208:211], v203 offset:50176
	ds_read_b128 v[212:215], v203 offset:51200
	ds_read_b128 v[216:219], v203 offset:52224
	ds_read_b128 v[220:223], v203 offset:53248
	ds_read_b128 v[224:227], v203 offset:54272
	ds_read_b128 v[228:231], v203 offset:55296
	ds_read_b128 v[232:235], v203 offset:56320
	global_load_lds_dwordx4 v[146:147], off
	s_add_i32 m0, s20, 0x2000
	s_add_u32 s18, s18, 0x100080
	v_lshl_add_u64 v[146:147], v[148:149], 0, s[38:39]
	s_addc_u32 s19, s19, 0
	s_add_i32 s20, s57, s24
	global_load_lds_dwordx4 v[146:147], off
	v_lshl_add_u64 v[146:147], s[18:19], 0, v[0:1]
	s_mov_b32 m0, s20
	s_nop 0
	global_load_lds_dwordx4 v[146:147], off
	v_lshl_add_u64 v[146:147], s[18:19], 0, v[154:155]
	s_add_i32 m0, s20, 0x2000
	s_nop 0
	global_load_lds_dwordx4 v[146:147], off
	v_lshl_add_u64 v[146:147], v[180:181], 0, s[38:39]
	s_mov_b32 m0, s31
	s_nop 0
	global_load_lds_dwordx4 v[146:147], off
	v_lshl_add_u64 v[146:147], v[236:237], 0, s[38:39]
	s_mov_b32 m0, s33
	s_nop 0
	global_load_lds_dwordx4 v[146:147], off
	s_waitcnt vmcnt(8)
	s_waitcnt lgkmcnt(0)
	s_barrier
	s_setprio 1
	s_waitcnt lgkmcnt(0)
	v_mfma_f32_16x16x32_bf16 v[94:97], v[130:133], v[204:207], v[94:97]
	v_mfma_f32_16x16x32_bf16 v[90:93], v[138:141], v[204:207], v[90:93]
	v_mfma_f32_16x16x32_bf16 v[86:89], v[130:133], v[212:215], v[86:89]
	v_mfma_f32_16x16x32_bf16 v[82:85], v[138:141], v[212:215], v[82:85]
	v_mfma_f32_16x16x32_bf16 v[78:81], v[130:133], v[220:223], v[78:81]
	v_mfma_f32_16x16x32_bf16 v[74:77], v[138:141], v[220:223], v[74:77]
	v_mfma_f32_16x16x32_bf16 v[70:73], v[130:133], v[228:231], v[70:73]
	v_mfma_f32_16x16x32_bf16 v[66:69], v[138:141], v[228:231], v[66:69]
	v_mfma_f32_16x16x32_bf16 v[94:97], v[134:137], v[208:211], v[94:97]
	v_mfma_f32_16x16x32_bf16 v[90:93], v[142:145], v[208:211], v[90:93]
	v_mfma_f32_16x16x32_bf16 v[86:89], v[134:137], v[216:219], v[86:89]
	v_mfma_f32_16x16x32_bf16 v[82:85], v[142:145], v[216:219], v[82:85]
	v_mfma_f32_16x16x32_bf16 v[78:81], v[134:137], v[224:227], v[78:81]
	v_mfma_f32_16x16x32_bf16 v[74:77], v[142:145], v[224:227], v[74:77]
	v_mfma_f32_16x16x32_bf16 v[70:73], v[134:137], v[232:235], v[70:73]
	v_mfma_f32_16x16x32_bf16 v[66:69], v[142:145], v[232:235], v[66:69]
	s_setprio 0
	s_setprio 1
	v_mfma_f32_16x16x32_bf16 v[30:33], v[164:167], v[204:207], v[30:33]
	v_mfma_f32_16x16x32_bf16 v[26:29], v[172:175], v[204:207], v[26:29]
	v_mfma_f32_16x16x32_bf16 v[22:25], v[164:167], v[212:215], v[22:25]
	v_mfma_f32_16x16x32_bf16 v[18:21], v[172:175], v[212:215], v[18:21]
	v_mfma_f32_16x16x32_bf16 v[14:17], v[164:167], v[220:223], v[14:17]
	v_mfma_f32_16x16x32_bf16 v[10:13], v[172:175], v[220:223], v[10:13]
	v_mfma_f32_16x16x32_bf16 v[6:9], v[164:167], v[228:231], v[6:9]
	v_mfma_f32_16x16x32_bf16 v[2:5], v[172:175], v[228:231], v[2:5]
	v_mfma_f32_16x16x32_bf16 v[30:33], v[168:171], v[208:211], v[30:33]
	v_mfma_f32_16x16x32_bf16 v[26:29], v[176:179], v[208:211], v[26:29]
	v_mfma_f32_16x16x32_bf16 v[22:25], v[168:171], v[216:219], v[22:25]
	v_mfma_f32_16x16x32_bf16 v[18:21], v[176:179], v[216:219], v[18:21]
	v_mfma_f32_16x16x32_bf16 v[14:17], v[168:171], v[224:227], v[14:17]
	v_mfma_f32_16x16x32_bf16 v[10:13], v[176:179], v[224:227], v[10:13]
	v_mfma_f32_16x16x32_bf16 v[6:9], v[168:171], v[232:235], v[6:9]
	v_mfma_f32_16x16x32_bf16 v[2:5], v[176:179], v[232:235], v[2:5]
	s_setprio 0
	s_barrier
	s_add_i32 s55, s55, 2
	s_add_u32 s16, s16, 0x100
	s_addc_u32 s17, s17, 0
	s_add_u32 s53, s53, 0x100
	s_addc_u32 s54, s54, 0

; __device__ __forceinline__ void ml_phase_a(const Args& A, Frame& F0) {
;     ...
;     if ((int)blockIdx.x < 4096) MLA_LOAD((int)blockIdx.x);
;     for (int u = blockIdx.x; u < 4096; u += F.G) {
;         const int bh = u >> 7, c = u & 127, b = bh >> 3, h = bh & 7; const size_t t0 = (size_t)b * SEQ + (size_t)c * 64;
;         const float lf = log_sigmoid_f(pf_f + cw[4096 + h]);
;         const float bs = wave_scan_incl(lf, lane);
;         const float g = __shfl(bs, 63);
;         const float is = pf_i + cw[4104 + h];
;         const float a = g - bs + is; const float ma = wave_max(a); const float wk = fexp(a - ma);
;         if (wave == 0) { GB[u * 64 + lane] = bs; GI[u * 64 + lane] = is; if (lane == 0) { GSC[u * 4 + 0] = g; GSC[u * 4 + 1] = ma; } }
; #pragma unroll
;         for (int rep = 0; rep < 2; ++rep) {
;             const int idx = tid + rep * 512, s = idx >> 4, cgp = idx & 15;
;             const int col = (cgp < 8) ? h * 64 + cgp * 8 : 512 + h * 64 + (cgp - 8) * 8;
;             const float wks = __shfl(wk, s);
;             float acc[8];
; #pragma unroll
;             for (int e = 0; e < 8; ++e) acc[e] = 0.f;
; #pragma unroll
;             for (int j = 0; j < 4; ++j) { const int tt = c * 64 + s - 3 + j;
;                 if (tt >= 0) { const u32x4 raw = pc[rep][j];
;                     const f32x4 w0 = *(const LAS f32x4*)(cw + j * 1024 + col), w1 = *(const LAS f32x4*)(cw + j * 1024 + col + 4);
;                     acc[0] += w0.x * bflo(raw.x); acc[1] += w0.y * bfhi(raw.x); acc[2] += w0.z * bflo(raw.y); acc[3] += w0.w * bfhi(raw.y);
;                     acc[4] += w1.x * bflo(raw.z); acc[5] += w1.y * bfhi(raw.z); acc[6] += w1.z * bflo(raw.w); acc[7] += w1.w * bfhi(raw.w); } }
;             const float qs = (cgp < 8) ? 0.125f : 1.0f;
; #pragma unroll
;             for (int e = 0; e < 8; ++e) acc[e] = acc[e] * fsigmoid(acc[e]) * qs;
;             u32x4 o; o.x = pk2(acc[0], acc[1]); o.y = pk2(acc[2], acc[3]); o.z = pk2(acc[4], acc[5]); o.w = pk2(acc[6], acc[7]);
;             *(u32x4*)(QKC + (t0 + s) * 1024 + col) = o;
;             if (cgp >= 8) { u32x4 ow; ow.x = pk2(acc[0] * wks, acc[1] * wks); ow.y = pk2(acc[2] * wks, acc[3] * wks); ow.z = pk2(acc[4] * wks, acc[5] * wks); ow.w = pk2(acc[6] * wks, acc[7] * wks);
;                 *(LAS u32x4*)(Kw + s * KSTR + (cgp - 8) * 16) = ow; }
;         }
; #pragma unroll
.LBB0_782:
	s_and_b64 vcc, exec, s[0:1]
	s_cbranch_vccnz .LBB0_815
	v_add_u32_e32 v0, -1, v185
	v_cmp_lt_i32_e32 vcc, v0, v194
	s_cmp_lt_u32 s18, 64
	s_cselect_b64 s[4:5], -1, 0
	v_cndmask_b32_e32 v0, v0, v185, vcc
	v_lshlrev_b32_e32 v72, 2, v0
	v_add_u32_e32 v0, -2, v185
	v_cmp_lt_i32_e32 vcc, v0, v194
	s_ashr_i32 s19, s18, 8
	v_bfe_u32 v4, v58, 2, 2
	v_cndmask_b32_e32 v0, v0, v185, vcc
	v_lshlrev_b32_e32 v73, 2, v0
	v_add_u32_e32 v0, -4, v185
	v_cmp_lt_i32_e32 vcc, v0, v194
	s_lshl_b32 s20, s19, 6
	v_lshlrev_b32_e32 v10, 1, v58
	v_cndmask_b32_e32 v0, v0, v185, vcc
	v_lshlrev_b32_e32 v74, 2, v0
	v_add_u32_e32 v0, -8, v185
	v_cmp_lt_i32_e32 vcc, v0, v194
	v_lshlrev_b32_e32 v6, 3, v60
	s_bfe_u32 s18, s18, 0x20006
	v_cndmask_b32_e32 v0, v0, v185, vcc
	v_lshlrev_b32_e32 v75, 2, v0
	v_add_u32_e32 v0, -16, v185
	v_cmp_lt_i32_e32 vcc, v0, v194
	s_add_i32 s20, s20, 0
	v_and_b32_e32 v6, 24, v6
	v_cndmask_b32_e32 v0, v0, v185, vcc
	v_lshlrev_b32_e32 v76, 2, v0
	v_subrev_u32_e32 v0, 32, v185
	v_cmp_lt_i32_e32 vcc, v0, v194
	v_cmp_lt_u32_e64 s[16:17], 7, v3
	s_movk_i32 s21, 0xff80
	v_cndmask_b32_e32 v0, v0, v185, vcc
	v_cmp_lt_i32_e32 vcc, v192, v186
	v_lshlrev_b32_e32 v77, 2, v0
	v_add_u32_e32 v5, 0x1c0, v2
	v_cndmask_b32_e32 v0, v185, v192, vcc
	v_cmp_lt_i32_e32 vcc, v198, v186
	v_lshlrev_b32_e32 v79, 2, v0
	v_add_u32_e32 v85, 0, v10
	v_cndmask_b32_e32 v0, v185, v198, vcc
	v_cmp_lt_i32_e32 vcc, v252, v186
	v_lshlrev_b32_e32 v80, 2, v0
	v_cmp_eq_u32_e64 s[0:1], 0, v60
	v_cndmask_b32_e32 v0, v185, v252, vcc
	v_cmp_lt_i32_e32 vcc, v189, v186
	v_lshlrev_b32_e32 v81, 2, v0
	v_cmp_gt_u32_e64 s[6:7], 2, v60
	v_cndmask_b32_e32 v0, v185, v189, vcc
	v_cmp_lt_i32_e32 vcc, v188, v186
	v_lshlrev_b32_e32 v82, 2, v0
	v_cmp_gt_u32_e64 s[8:9], 4, v60
	v_cndmask_b32_e32 v0, v185, v188, vcc
	v_cmp_lt_i32_e32 vcc, v187, v186
	v_lshlrev_b32_e32 v83, 2, v0
	v_cmp_gt_u32_e64 s[10:11], 8, v60
	v_cndmask_b32_e32 v0, v185, v187, vcc
	v_lshlrev_b32_e32 v84, 2, v0
	v_cmp_gt_u32_e32 vcc, 8, v3
	v_mov_b32_e32 v0, 0x3e000000
	v_lshl_add_u32 v3, v3, 4, 0
	v_cndmask_b32_e32 v66, 1.0, v0, vcc
	v_lshlrev_b32_e32 v0, 4, v58
	v_and_b32_e32 v0, 0xf0, v0
	v_add_u32_e32 v8, 0, v0
	v_lshrrev_b32_e32 v0, 5, v60
	v_lshl_or_b32 v9, v0, 3, v4
	v_and_b32_e32 v4, 32, v10
	v_add3_u32 v11, s20, v4, v6
	s_lshl_b32 s20, s18, 6
	s_add_i32 s20, s20, 0
	v_lshlrev_b32_e32 v0, 2, v0
	v_add3_u32 v12, s20, v4, v6
	v_lshl_or_b32 v4, s19, 5, v0
	v_lshlrev_b32_e32 v0, 7, v60
	v_and_b32_e32 v0, 0xf80, v0
	v_lshl_or_b32 v0, s18, 12, v0
	v_readlane_b32 s18, v253, 50
	v_readlane_b32 s19, v253, 51
	s_movk_i32 s20, 0x90
	v_cndmask_b32_e32 v87, v5, v2, vcc
	v_lshl_add_u64 v[6:7], s[18:19], 0, v[0:1]
	v_and_or_b32 v0, v62, 63, v194
	v_lshlrev_b32_e32 v86, 2, v0
	v_mul_lo_u32 v0, v62, s20
	v_add3_u32 v88, v3, v0, s21
	v_and_or_b32 v0, v64, 63, v194
	v_lshlrev_b32_e32 v89, 2, v0
	v_mul_lo_u32 v0, v64, s20
	s_movk_i32 s20, 0x110
	v_add3_u32 v90, v3, v0, s21
	v_mul_lo_u32 v0, v62, s20
	v_mul_lo_u32 v3, v64, s20
	v_mul_u32_u24_e32 v10, 0x90, v9
	v_mul_u32_u24_e32 v9, 0x110, v9
	v_ashrrev_i32_e32 v5, 31, v4
	v_cmp_gt_u32_e64 s[12:13], 16, v60
	v_cmp_gt_u32_e64 s[14:15], 32, v60
	v_lshl_or_b32 v78, v185, 2, v196
	v_cmp_gt_i32_e64 s[18:19], 64, v58
	v_ashrrev_i32_e32 v65, 31, v64
	v_lshl_add_u64 v[68:69], v[4:5], 1, v[6:7]
	v_mov_b32_e32 v67, v66
	v_add_u32_e32 v91, v8, v0
	v_add_u32_e32 v92, v8, v3
	v_lshlrev_b32_e32 v70, 1, v2
	v_add_u32_e32 v93, v11, v10
	v_add_u32_e32 v94, v12, v9
	s_mov_b32 s20, s2
	s_waitcnt vmcnt(0)
	s_branch .LBB0_785

; __device__ __forceinline__ float fexp(float x) { return __builtin_amdgcn_exp2f(LOG2E * x); }
; __device__ __forceinline__ float log_sigmoid_f(float x) { return fminf(x, 0.f) - 0.6931471805599453f * __builtin_amdgcn_logf(1.0f + __builtin_amdgcn_exp2f(-LOG2E * fabsf(x))); }
; __device__ __forceinline__ void ml_phase_a(const Args& A, Frame& F0) {
;     ...
;         const int bh = u >> 7, c = u & 127, b = bh >> 3, h = bh & 7; const size_t t0 = (size_t)b * SEQ + (size_t)c * 64;
;         const float lf = log_sigmoid_f(pf_f + cw[4096 + h]);
;         const float bs = wave_scan_incl(lf, lane);
;         const float g = __shfl(bs, 63);
;         const float is = pf_i + cw[4104 + h];
;         const float a = g - bs + is; const float ma = wave_max(a); const float wk = fexp(a - ma);
;         if (wave == 0) { GB[u * 64 + lane] = bs; GI[u * 64 + lane] = is; if (lane == 0) { GSC[u * 4 + 0] = g; GSC[u * 4 + 1] = ma; } }
.LBB0_785:
	s_bfe_u32 s24, s20, 0x30007
	s_lshl_b32 s21, s24, 2
	s_add_i32 s21, s21, 0
	v_mov_b32_e32 v0, s21
	v_add_u32_e32 v0, 0xc000, v0
	ds_read2_b32 v[2:3], v0 offset1:8
	s_mov_b32 s21, 0xbfb8aa3b
	s_lshl_b32 s28, s20, 6
	s_andn2_b64 vcc, exec, s[4:5]
	s_waitcnt vmcnt(4) lgkmcnt(0)
	v_add_f32_e32 v0, v61, v2
	v_mul_f32_e64 v2, |v0|, s21
	v_exp_f32_e32 v2, v2
	v_min_f32_e32 v0, 0, v0
	v_add_f32_e32 v4, v59, v3
	v_add_f32_e32 v2, 1.0, v2
	v_log_f32_e32 v2, v2
	s_nop 0
	v_fmac_f32_e32 v0, 0xbf317218, v2
	ds_bpermute_b32 v2, v72, v0
	s_waitcnt lgkmcnt(0)
	v_add_f32_e32 v2, v0, v2
	v_cndmask_b32_e64 v0, v2, v0, s[0:1]
	ds_bpermute_b32 v2, v73, v0
	s_waitcnt lgkmcnt(0)
	v_add_f32_e32 v2, v0, v2
	v_cndmask_b32_e64 v0, v2, v0, s[6:7]
	ds_bpermute_b32 v2, v74, v0
	s_waitcnt lgkmcnt(0)
	v_add_f32_e32 v2, v0, v2
	v_cndmask_b32_e64 v0, v2, v0, s[8:9]
	ds_bpermute_b32 v2, v75, v0
	s_waitcnt lgkmcnt(0)
	v_add_f32_e32 v2, v0, v2
	v_cndmask_b32_e64 v0, v2, v0, s[10:11]
	ds_bpermute_b32 v2, v76, v0
	s_waitcnt lgkmcnt(0)
	v_add_f32_e32 v2, v0, v2
	v_cndmask_b32_e64 v0, v2, v0, s[12:13]
	ds_bpermute_b32 v2, v77, v0
	s_waitcnt lgkmcnt(0)
	v_add_f32_e32 v2, v0, v2
	v_cndmask_b32_e64 v5, v2, v0, s[14:15]
	ds_bpermute_b32 v2, v78, v5
	s_waitcnt lgkmcnt(0)
	v_sub_f32_e32 v0, v2, v5
	v_add_f32_e32 v0, v4, v0
	ds_bpermute_b32 v3, v79, v0
	s_waitcnt lgkmcnt(0)
	v_max_f32_e32 v3, v3, v3
	v_max_f32_e32 v3, v0, v3
	ds_bpermute_b32 v6, v80, v3
	s_waitcnt lgkmcnt(0)
	v_max_f32_e32 v6, v6, v6
	v_max_f32_e32 v3, v3, v6
	ds_bpermute_b32 v6, v81, v3
	s_waitcnt lgkmcnt(0)
	v_max_f32_e32 v6, v6, v6
	v_max_f32_e32 v3, v3, v6
	ds_bpermute_b32 v6, v82, v3
	s_waitcnt lgkmcnt(0)
	v_max_f32_e32 v6, v6, v6
	v_max_f32_e32 v3, v3, v6
	ds_bpermute_b32 v6, v83, v3
	s_waitcnt lgkmcnt(0)
	v_max_f32_e32 v6, v6, v6
	v_max_f32_e32 v3, v3, v6
	ds_bpermute_b32 v6, v84, v3
	s_waitcnt lgkmcnt(0)
	v_max_f32_e32 v6, v6, v6
	v_max_f32_e32 v3, v3, v6
	s_cbranch_vccnz .LBB0_789
	v_or_b32_e32 v6, s28, v60
	v_ashrrev_i32_e32 v7, 31, v6
	v_readlane_b32 s22, v253, 35
	v_lshlrev_b64 v[6:7], 2, v[6:7]
	v_readlane_b32 s23, v253, 36
	s_nop 1
	v_lshl_add_u64 v[8:9], s[22:23], 0, v[6:7]
	v_readlane_b32 s22, v253, 37
	v_readlane_b32 s23, v253, 38
	global_store_dword v[8:9], v5, off
	s_nop 0
	v_lshl_add_u64 v[6:7], s[22:23], 0, v[6:7]
	global_store_dword v[6:7], v4, off
	s_and_saveexec_b64 s[22:23], s[0:1]
	s_cbranch_execz .LBB0_788
	s_lshl_b32 s26, s20, 2
	s_ashr_i32 s27, s26, 31
	s_lshl_b64 s[26:27], s[26:27], 2
	v_readlane_b32 s21, v253, 54
	s_add_u32 s26, s21, s26
	v_readlane_b32 s21, v253, 55
	s_addc_u32 s27, s21, s27
	global_store_dwordx2 v1, v[2:3], s[26:27]

; #define PG8_STAGE(bufoff, gbase, voff) do { _Pragma("unroll") for (int _i = 0; _i < 2; ++_i) \
;         __builtin_amdgcn_global_load_lds((const unsigned*)((const char*)(gbase) + (voff)[_i]), (PG8_LAS unsigned*)(lds + (bufoff) + ldsw + _i * 8192), 16, 0, 0); } while (0)
; #define PG8_WAIT_V(n) asm volatile("s_waitcnt vmcnt(" #n ")" ::: "memory")
; #define PG8_BAR __builtin_amdgcn_s_barrier()
; template <class Epi, class Sched, bool ALIGN_EPI = false, bool SP2 = false>
; __device__ __forceinline__ void gemm_phase(PG8_LAS unsigned char* lds, const Gemm g, const Sched& S, const Epi& E) {
;     ...
;     const int aoff = lds_byte(wr * 64 + fr, fq * 8), boff = lds_byte(wc * 32 + fr, fq * 8);
;     ...
;     Unit cur, nxt; int ui = 0;
;     if (!S.next(0, cur)) return;
;     f32x4 acc[2][2][4][2];
; #pragma unroll
;     for (int a = 0; a < 2; ++a)
; #pragma unroll
;         for (int b = 0; b < 2; ++b)
; #pragma unroll
;             for (int m = 0; m < 4; ++m)
; #pragma unroll
;                 for (int n = 0; n < 2; ++n) acc[a][b][m][n] = (f32x4){0.f, 0.f, 0.f, 0.f};
;     bf16x8 At[4][2], B0[2][2], B1[2][2];
;     const char* cA = (const char*)g.A + (size_t)cur.pm * tstep; const char* cB = (const char*)g.Bt + (size_t)cur.pn * tstep;
;     S.a_ready(cur);
;     if constexpr (SP2) {
;         PG8_STAGE(PG8_SB(0, 0), cB, voffB); PG8_STAGE(PG8_SB(0, 1), cB + hstep, voffB); PG8_STAGE(PG8_SA(0, 0), cA, voffA); PG8_STAGE(PG8_SA(0, 1), cA + hstep, voffA);
;         if (wr == 1) PG8_BAR;
;         PG8_WAIT_V(2); PG8_BAR;
;         PG8_STAGE(PG8_SB(1, 0), cB + kstep, voffB); PG8_STAGE(PG8_SA(1, 0), cA + kstep, voffA); PG8_STAGE(PG8_SB(1, 1), cB + hstep + kstep, voffB);
;         PG8_WAIT_V(6); PG8_BAR;
.LBB0_1080:
	v_readlane_b32 s7, v255, 2
	s_waitcnt vmcnt(0)
	v_lshrrev_b32_e32 v18, 1, v12
	s_add_u32 s29, s7, 0x5000
	v_readlane_b32 s7, v255, 3
	v_and_b32_e32 v18, 24, v18
	v_readlane_b32 s16, v254, 10
	s_addc_u32 s30, s7, 0
	v_and_b32_e32 v13, 15, v12
	v_lshlrev_b32_e32 v19, 1, v18
	v_lshlrev_b32_e32 v12, 2, v12
	s_lshl_b32 s5, s5, 5
	v_mov_b32_e32 v135, v1
	v_readlane_b32 s17, v254, 11
	v_lshl_or_b32 v166, s6, 6, v13
	v_lshl_or_b32 v13, v13, 6, v19
	s_lshl_b32 s6, s6, 13
	v_and_b32_e32 v12, 32, v12
	s_and_b32 s5, s5, 0x60
	s_add_i32 m0, s25, 0x18000
	v_lshl_add_u64 v[2:3], v[2:3], 0, s[38:39]
	v_lshl_add_u64 v[14:15], s[16:17], 0, v[134:135]
	v_mov_b32_e32 v133, v1
	v_bitop3_b32 v19, v13, s6, v12 bitop3:0xde
	s_lshl_b32 s6, s5, 7
	s_waitcnt vmcnt(2)
	s_barrier
	global_load_lds_dwordx4 v[2:3], off
	v_lshl_add_u64 v[2:3], v[4:5], 0, s[38:39]
	s_add_i32 m0, s25, 0x1a000
	s_add_i32 s31, s25, 0x8000
	s_add_i32 s33, s25, 0xa000
	v_lshl_add_u64 v[16:17], s[16:17], 0, v[132:133]
	v_bitop3_b32 v167, v13, s6, v12 bitop3:0xde
	global_load_lds_dwordx4 v[2:3], off
	v_lshl_add_u64 v[2:3], v[14:15], 0, s[38:39]
	s_mov_b32 m0, s31
	s_add_u32 s6, s18, 0x40080
	global_load_lds_dwordx4 v[2:3], off
	v_lshl_add_u64 v[2:3], v[16:17], 0, s[38:39]
	s_mov_b32 m0, s33
	s_addc_u32 s7, s19, 0
	global_load_lds_dwordx4 v[2:3], off
	s_add_i32 m0, s25, 0x1c000
	v_lshl_add_u64 v[2:3], s[6:7], 0, v[0:1]
	global_load_lds_dwordx4 v[2:3], off
	v_lshl_add_u64 v[2:3], s[6:7], 0, v[130:131]
	s_add_i32 m0, s25, 0x1e000
	s_cmpk_lt_u32 s4, 0x100
	global_load_lds_dwordx4 v[2:3], off
	v_lshlrev_b32_e32 v2, 14, v10
	v_and_b32_e32 v2, 0xffff8000, v2
	v_lshl_add_u32 v2, v9, 11, v2
	v_and_b32_e32 v3, 1, v10
	v_lshl_or_b32 v2, v3, 6, v2
	v_lshl_add_u32 v136, v11, 1, v2
	v_lshlrev_b32_e32 v2, 14, v6
	v_and_b32_e32 v2, 0xffff8000, v2
	s_waitcnt vmcnt(6)
	v_lshl_add_u32 v2, v7, 11, v2
	v_and_b32_e32 v3, 1, v6
	v_or_b32_e32 v168, s5, v18
	v_lshl_or_b32 v2, v3, 6, v2
	v_readlane_b32 s4, v254, 16
	s_cselect_b64 s[6:7], -1, 0
	v_mov_b32_e32 v137, v1
	v_lshl_add_u32 v138, v8, 1, v2
	v_mov_b32_e32 v139, v1
	s_mov_b32 s34, 0
	v_add_u32_e32 v169, 0, v19
	v_readlane_b32 s44, v254, 7
	s_mov_b32 s35, s4
	s_barrier
	v_readlane_b32 s5, v254, 17
	s_waitcnt vmcnt(0)
	s_branch .LBB0_1083

; #define PG8_STAGE(bufoff, gbase, voff) do { _Pragma("unroll") for (int _i = 0; _i < 2; ++_i) \
;         __builtin_amdgcn_global_load_lds((const unsigned*)((const char*)(gbase) + (voff)[_i]), (PG8_LAS unsigned*)(lds + (bufoff) + ldsw + _i * 8192), 16, 0, 0); } while (0)
; #define PG8_LDA(dst, b, h) do { _Pragma("unroll") for (int m = 0; m < 4; ++m) _Pragma("unroll") for (int k = 0; k < 2; ++k) dst[m][k] = *(const PG8_LAS bf16x8*)(lds + PG8_SA(b, h) + aoff + m * 2048 + k * 1024); } while (0)
; #define PG8_LDB(dst, b, h) do { _Pragma("unroll") for (int n = 0; n < 2; ++n) _Pragma("unroll") for (int k = 0; k < 2; ++k) dst[n][k] = *(const PG8_LAS bf16x8*)(lds + PG8_SB(b, h) + boff + n * 2048 + k * 1024); } while (0)
; #define PG8_MMA(ai, bj, At, Bt) do { __builtin_amdgcn_s_setprio(1); _Pragma("unroll") for (int m = 0; m < 4; ++m) _Pragma("unroll") for (int n = 0; n < 2; ++n) _Pragma("unroll") for (int k = 0; k < 2; ++k) \
;         acc[ai][bj][m][n] = __builtin_amdgcn_mfma_f32_16x16x32_bf16(Bt[n][k], At[m][k], acc[ai][bj][m][n], 0, 0, 0); __builtin_amdgcn_s_setprio(0); } while (0)
; #define PG8_BAR __builtin_amdgcn_s_barrier()
; template <class Epi, class Sched, bool ALIGN_EPI = false, bool SP2 = false>
; __device__ __forceinline__ void gemm_phase(PG8_LAS unsigned char* lds, const Gemm g, const Sched& S, const Epi& E) {
;     ...
;         const bool has_next = S.next(ui + 1, nxt);
;         const char* nA = has_next ? (const char*)g.A + (size_t)nxt.pm * tstep : cA; const char* nB = has_next ? (const char*)g.Bt + (size_t)nxt.pn * tstep : cB;
;         for (int t = 0; t < nt; t += 2) {
;             const bool last = (t == nt - 2);
;             const char* a1 = cA + (size_t)(t + 1) * kstep;
;             const char* a2 = last ? nA : cA + (size_t)(t + 2) * kstep; const char* b2 = last ? nB : cB + (size_t)(t + 2) * kstep;
;             const char* a3 = a2 + kstep; const char* b3 = b2 + kstep;
;             if (last && has_next) S.a_ready(nxt);
;             if constexpr (SP2) {
;             PG8_LDB(B0, 0, 0); PG8_LDB(B1, 0, 1); PG8_SCHED; PG8_LDA(At, 0, 0); PG8_STAGE(PG8_SA(1, 1), a1 + hstep, voffA);
;             PG8_WAIT_V(8); PG8_WAIT_L(0); PG8_BAR; PG8_MMA(0, 0, At, B0); PG8_MMA(0, 1, At, B1); PG8_BAR; PG8_SCHED;
;             PG8_LDA(At, 0, 1); PG8_STAGE(PG8_SB(0, 0), b2, voffB); PG8_STAGE(PG8_SB(0, 1), b2 + hstep, voffB); PG8_STAGE(PG8_SA(0, 0), a2, voffA);
.LBB0_1089:
	s_ashr_i32 s11, s10, 31
	s_lshl_b64 s[12:13], s[10:11], 19
	s_add_u32 s12, s90, s12
	s_addc_u32 s13, s91, s13
	s_and_b64 s[14:15], s[4:5], exec
	s_cselect_b32 s11, s13, s17
	s_cselect_b32 s45, s12, s16
	s_ashr_i32 s9, s8, 31
	s_lshl_b64 s[14:15], s[8:9], 19
	s_add_u32 s14, s22, s14
	s_addc_u32 s15, s23, s15
	s_and_b64 s[20:21], s[4:5], exec
	s_cselect_b32 s9, s15, s19
	s_cselect_b32 s46, s14, s18
	s_add_u32 s16, s16, 0x40080
	s_addc_u32 s17, s17, 0
	s_add_u32 s47, s18, 0x100
	s_addc_u32 s48, s19, 0
	s_mov_b32 s49, -2
	s_add_u32 s18, s16, 0xfffc0080
	s_addc_u32 s19, s17, -1
	s_add_i32 s50, 0, 0x10000
	s_cmp_eq_u32 s49, 12
	s_cselect_b32 s21, s11, s19
	s_cselect_b32 s20, s45, s18
	v_add_u32_e32 v148, s50, v167
	s_cselect_b32 s19, s9, s48
	s_cselect_b32 s18, s46, s47
	s_add_i32 s52, 0, 0x14000
	ds_read_b128 v[140:143], v148
	ds_read_b128 v[144:147], v148 offset:1024
	ds_read_b128 v[154:157], v148 offset:2048
	ds_read_b128 v[158:161], v148 offset:3072
	v_add_u32_e32 v148, s52, v167
	ds_read_b128 v[162:165], v148
	ds_read_b128 v[170:173], v148 offset:1024
	ds_read_b128 v[174:177], v148 offset:2048
	ds_read_b128 v[178:181], v148 offset:3072
	v_lshl_add_u64 v[148:149], s[16:17], 0, v[136:137]
	s_add_i32 m0, s25, 0xc000
	ds_read_b128 v[200:203], v169
	ds_read_b128 v[204:207], v169 offset:1024
	ds_read_b128 v[208:211], v169 offset:2048
	ds_read_b128 v[212:215], v169 offset:3072
	ds_read_b128 v[216:219], v169 offset:4096
	ds_read_b128 v[220:223], v169 offset:5120
	ds_read_b128 v[224:227], v169 offset:6144
	ds_read_b128 v[228:231], v169 offset:7168
	global_load_lds_dwordx4 v[148:149], off
	v_lshl_add_u64 v[148:149], s[16:17], 0, v[138:139]
	s_add_i32 m0, s25, 0xe000
	s_nop 0
	global_load_lds_dwordx4 v[148:149], off
	s_waitcnt vmcnt(20)
	s_waitcnt lgkmcnt(0)
	s_barrier
	s_setprio 1
	s_waitcnt lgkmcnt(0)
	v_mfma_f32_16x16x32_bf16 v[126:129], v[140:143], v[200:203], 0
	v_mfma_f32_16x16x32_bf16 v[122:125], v[154:157], v[200:203], 0
	v_mfma_f32_16x16x32_bf16 v[118:121], v[140:143], v[208:211], 0
	v_mfma_f32_16x16x32_bf16 v[114:117], v[154:157], v[208:211], 0
	v_mfma_f32_16x16x32_bf16 v[110:113], v[140:143], v[216:219], 0
	v_mfma_f32_16x16x32_bf16 v[106:109], v[154:157], v[216:219], 0
	v_mfma_f32_16x16x32_bf16 v[102:105], v[140:143], v[224:227], 0
	v_mfma_f32_16x16x32_bf16 v[98:101], v[154:157], v[224:227], 0
	v_mfma_f32_16x16x32_bf16 v[126:129], v[144:147], v[204:207], v[126:129]
	v_mfma_f32_16x16x32_bf16 v[122:125], v[158:161], v[204:207], v[122:125]
	v_mfma_f32_16x16x32_bf16 v[118:121], v[144:147], v[212:215], v[118:121]
	v_mfma_f32_16x16x32_bf16 v[114:117], v[158:161], v[212:215], v[114:117]
	v_mfma_f32_16x16x32_bf16 v[110:113], v[144:147], v[220:223], v[110:113]
	v_mfma_f32_16x16x32_bf16 v[106:109], v[158:161], v[220:223], v[106:109]
	v_mfma_f32_16x16x32_bf16 v[102:105], v[144:147], v[228:231], v[102:105]
	v_mfma_f32_16x16x32_bf16 v[98:101], v[158:161], v[228:231], v[98:101]
	s_setprio 0
	s_setprio 1
	v_mfma_f32_16x16x32_bf16 v[62:65], v[162:165], v[200:203], 0
	v_mfma_f32_16x16x32_bf16 v[58:61], v[174:177], v[200:203], 0
	v_mfma_f32_16x16x32_bf16 v[54:57], v[162:165], v[208:211], 0
	v_mfma_f32_16x16x32_bf16 v[50:53], v[174:177], v[208:211], 0
	v_mfma_f32_16x16x32_bf16 v[46:49], v[162:165], v[216:219], 0
	v_mfma_f32_16x16x32_bf16 v[42:45], v[174:177], v[216:219], 0
	v_mfma_f32_16x16x32_bf16 v[38:41], v[162:165], v[224:227], 0
	v_mfma_f32_16x16x32_bf16 v[34:37], v[174:177], v[224:227], 0
	v_mfma_f32_16x16x32_bf16 v[62:65], v[170:173], v[204:207], v[62:65]
	v_mfma_f32_16x16x32_bf16 v[58:61], v[178:181], v[204:207], v[58:61]
	v_mfma_f32_16x16x32_bf16 v[54:57], v[170:173], v[212:215], v[54:57]
	v_mfma_f32_16x16x32_bf16 v[50:53], v[178:181], v[212:215], v[50:53]
	v_mfma_f32_16x16x32_bf16 v[46:49], v[170:173], v[220:223], v[46:49]
	v_mfma_f32_16x16x32_bf16 v[42:45], v[178:181], v[220:223], v[42:45]
	v_mfma_f32_16x16x32_bf16 v[38:41], v[170:173], v[228:231], v[38:41]
	v_mfma_f32_16x16x32_bf16 v[34:37], v[178:181], v[228:231], v[34:37]
	s_setprio 0
	s_barrier
	s_add_i32 s50, s50, s24
	v_lshl_add_u64 v[148:149], s[18:19], 0, v[0:1]
	s_mov_b32 m0, s50
	ds_read_b128 v[200:203], v169 offset:16384
	ds_read_b128 v[204:207], v169 offset:17408
	ds_read_b128 v[208:211], v169 offset:18432
	ds_read_b128 v[212:215], v169 offset:19456
	ds_read_b128 v[216:219], v169 offset:20480
	ds_read_b128 v[220:223], v169 offset:21504
	ds_read_b128 v[224:227], v169 offset:22528
	ds_read_b128 v[228:231], v169 offset:23552
	global_load_lds_dwordx4 v[148:149], off
	s_add_i32 m0, s50, 0x2000
	s_add_u32 s50, s18, 0x40000
	v_lshl_add_u64 v[232:233], s[18:19], 0, v[130:131]
	s_addc_u32 s51, s19, 0
	s_add_i32 s52, s52, s24
	global_load_lds_dwordx4 v[232:233], off
	v_lshl_add_u64 v[234:235], s[50:51], 0, v[0:1]
	s_mov_b32 m0, s52
	v_lshl_add_u64 v[236:237], s[20:21], 0, v[132:133]
	global_load_lds_dwordx4 v[234:235], off
	v_lshl_add_u64 v[234:235], s[50:51], 0, v[130:131]
	s_add_i32 m0, s52, 0x2000
	s_nop 0
	global_load_lds_dwordx4 v[234:235], off
	v_lshl_add_u64 v[234:235], s[20:21], 0, v[134:135]
	s_mov_b32 m0, s25
	s_nop 0
	global_load_lds_dwordx4 v[234:235], off
	s_mov_b32 m0, s26
	s_nop 0
	global_load_lds_dwordx4 v[236:237], off
	s_waitcnt vmcnt(20)
	s_waitcnt lgkmcnt(0)
	s_barrier
; #define PG8_STAGE(bufoff, gbase, voff) do { _Pragma("unroll") for (int _i = 0; _i < 2; ++_i) \
;         __builtin_amdgcn_global_load_lds((const unsigned*)((const char*)(gbase) + (voff)[_i]), (PG8_LAS unsigned*)(lds + (bufoff) + ldsw + _i * 8192), 16, 0, 0); } while (0)
; #define PG8_LDA(dst, b, h) do { _Pragma("unroll") for (int m = 0; m < 4; ++m) _Pragma("unroll") for (int k = 0; k < 2; ++k) dst[m][k] = *(const PG8_LAS bf16x8*)(lds + PG8_SA(b, h) + aoff + m * 2048 + k * 1024); } while (0)
; #define PG8_LDB(dst, b, h) do { _Pragma("unroll") for (int n = 0; n < 2; ++n) _Pragma("unroll") for (int k = 0; k < 2; ++k) dst[n][k] = *(const PG8_LAS bf16x8*)(lds + PG8_SB(b, h) + boff + n * 2048 + k * 1024); } while (0)
; #define PG8_MMA(ai, bj, At, Bt) do { __builtin_amdgcn_s_setprio(1); _Pragma("unroll") for (int m = 0; m < 4; ++m) _Pragma("unroll") for (int n = 0; n < 2; ++n) _Pragma("unroll") for (int k = 0; k < 2; ++k) \
;         acc[ai][bj][m][n] = __builtin_amdgcn_mfma_f32_16x16x32_bf16(Bt[n][k], At[m][k], acc[ai][bj][m][n], 0, 0, 0); __builtin_amdgcn_s_setprio(0); } while (0)
; #define PG8_WAIT_V(n) asm volatile("s_waitcnt vmcnt(" #n ")" ::: "memory")
; #define PG8_WAIT_L(n) asm volatile("s_waitcnt lgkmcnt(" #n ")" ::: "memory")
; #define PG8_BAR __builtin_amdgcn_s_barrier()
; #define PG8_SCHED __builtin_amdgcn_sched_barrier(0)
; template <class Epi, class Sched, bool ALIGN_EPI = false, bool SP2 = false>
; __device__ __forceinline__ void gemm_phase(PG8_LAS unsigned char* lds, const Gemm g, const Sched& S, const Epi& E) {
;     ...
;             PG8_WAIT_V(8); PG8_WAIT_L(0); PG8_BAR; PG8_MMA(1, 0, At, B0); PG8_MMA(1, 1, At, B1); PG8_BAR; PG8_SCHED;
;             PG8_LDB(B0, 1, 0); PG8_LDB(B1, 1, 1); PG8_SCHED; PG8_LDA(At, 1, 0); PG8_STAGE(PG8_SA(0, 1), a2 + hstep, voffA);
;             PG8_WAIT_V(8); PG8_WAIT_L(0); PG8_BAR; PG8_MMA(0, 0, At, B0); PG8_MMA(0, 1, At, B1); PG8_BAR; PG8_SCHED;
;             PG8_LDA(At, 1, 1); PG8_STAGE(PG8_SB(1, 0), b3, voffB); PG8_STAGE(PG8_SB(1, 1), b3 + hstep, voffB); PG8_STAGE(PG8_SA(1, 0), a3, voffA);
	s_setprio 1
	s_waitcnt lgkmcnt(0)
	v_mfma_f32_16x16x32_bf16 v[94:97], v[140:143], v[200:203], 0
	v_mfma_f32_16x16x32_bf16 v[90:93], v[154:157], v[200:203], 0
	v_mfma_f32_16x16x32_bf16 v[86:89], v[140:143], v[208:211], 0
	v_mfma_f32_16x16x32_bf16 v[82:85], v[154:157], v[208:211], 0
	v_mfma_f32_16x16x32_bf16 v[78:81], v[140:143], v[216:219], 0
	v_mfma_f32_16x16x32_bf16 v[74:77], v[154:157], v[216:219], 0
	v_mfma_f32_16x16x32_bf16 v[70:73], v[140:143], v[224:227], 0
	v_mfma_f32_16x16x32_bf16 v[66:69], v[154:157], v[224:227], 0
	v_mfma_f32_16x16x32_bf16 v[94:97], v[144:147], v[204:207], v[94:97]
	v_mfma_f32_16x16x32_bf16 v[90:93], v[158:161], v[204:207], v[90:93]
	v_mfma_f32_16x16x32_bf16 v[86:89], v[144:147], v[212:215], v[86:89]
	v_mfma_f32_16x16x32_bf16 v[82:85], v[158:161], v[212:215], v[82:85]
	v_mfma_f32_16x16x32_bf16 v[78:81], v[144:147], v[220:223], v[78:81]
	v_mfma_f32_16x16x32_bf16 v[74:77], v[158:161], v[220:223], v[74:77]
	v_mfma_f32_16x16x32_bf16 v[70:73], v[144:147], v[228:231], v[70:73]
	v_mfma_f32_16x16x32_bf16 v[66:69], v[158:161], v[228:231], v[66:69]
	s_setprio 0
	s_setprio 1
	v_mfma_f32_16x16x32_bf16 v[30:33], v[162:165], v[200:203], 0
	v_mfma_f32_16x16x32_bf16 v[26:29], v[174:177], v[200:203], 0
	v_mfma_f32_16x16x32_bf16 v[22:25], v[162:165], v[208:211], 0
	v_mfma_f32_16x16x32_bf16 v[18:21], v[174:177], v[208:211], 0
	v_mfma_f32_16x16x32_bf16 v[14:17], v[162:165], v[216:219], 0
	v_mfma_f32_16x16x32_bf16 v[10:13], v[174:177], v[216:219], 0
	v_mfma_f32_16x16x32_bf16 v[6:9], v[162:165], v[224:227], 0
	v_mfma_f32_16x16x32_bf16 v[2:5], v[174:177], v[224:227], 0
	v_mfma_f32_16x16x32_bf16 v[30:33], v[170:173], v[204:207], v[30:33]
	v_mfma_f32_16x16x32_bf16 v[26:29], v[178:181], v[204:207], v[26:29]
	v_mfma_f32_16x16x32_bf16 v[22:25], v[170:173], v[212:215], v[22:25]
	v_mfma_f32_16x16x32_bf16 v[18:21], v[178:181], v[212:215], v[18:21]
	v_mfma_f32_16x16x32_bf16 v[14:17], v[170:173], v[220:223], v[14:17]
	v_mfma_f32_16x16x32_bf16 v[10:13], v[178:181], v[220:223], v[10:13]
	v_mfma_f32_16x16x32_bf16 v[6:9], v[170:173], v[228:231], v[6:9]
	v_mfma_f32_16x16x32_bf16 v[2:5], v[178:181], v[228:231], v[2:5]
	s_setprio 0
	s_barrier
	s_add_i32 s50, 0, 0x18000
	s_add_i32 s51, 0, 0x1c000
	v_add_u32_e32 v158, s50, v167
	v_add_u32_e32 v178, s51, v167
	ds_read_b128 v[140:143], v158
	ds_read_b128 v[144:147], v158 offset:1024
	ds_read_b128 v[154:157], v158 offset:2048
	ds_read_b128 v[158:161], v158 offset:3072
	ds_read_b128 v[162:165], v178
	ds_read_b128 v[170:173], v178 offset:1024
	ds_read_b128 v[174:177], v178 offset:2048
	ds_read_b128 v[178:181], v178 offset:3072
	s_add_u32 s20, s20, 0x40000
	s_addc_u32 s21, s21, 0
	s_mov_b32 m0, s27
	v_lshl_add_u64 v[238:239], s[20:21], 0, v[134:135]
	ds_read_b128 v[200:203], v169 offset:32768
	ds_read_b128 v[204:207], v169 offset:33792
	ds_read_b128 v[208:211], v169 offset:34816
	ds_read_b128 v[212:215], v169 offset:35840
	ds_read_b128 v[216:219], v169 offset:36864
	ds_read_b128 v[220:223], v169 offset:37888
	ds_read_b128 v[224:227], v169 offset:38912
	ds_read_b128 v[228:231], v169 offset:39936
	global_load_lds_dwordx4 v[238:239], off
	v_lshl_add_u64 v[238:239], s[20:21], 0, v[132:133]
	s_mov_b32 m0, s28
	s_nop 0
	global_load_lds_dwordx4 v[238:239], off
	s_waitcnt vmcnt(8)
	s_waitcnt lgkmcnt(0)
	s_barrier
	s_setprio 1
	s_waitcnt lgkmcnt(0)
	v_mfma_f32_16x16x32_bf16 v[126:129], v[140:143], v[200:203], v[126:129]
	v_mfma_f32_16x16x32_bf16 v[122:125], v[154:157], v[200:203], v[122:125]
	v_mfma_f32_16x16x32_bf16 v[118:121], v[140:143], v[208:211], v[118:121]
	v_mfma_f32_16x16x32_bf16 v[114:117], v[154:157], v[208:211], v[114:117]
	v_mfma_f32_16x16x32_bf16 v[110:113], v[140:143], v[216:219], v[110:113]
	v_mfma_f32_16x16x32_bf16 v[106:109], v[154:157], v[216:219], v[106:109]
	v_mfma_f32_16x16x32_bf16 v[102:105], v[140:143], v[224:227], v[102:105]
	v_mfma_f32_16x16x32_bf16 v[98:101], v[154:157], v[224:227], v[98:101]
	v_mfma_f32_16x16x32_bf16 v[126:129], v[144:147], v[204:207], v[126:129]
	v_mfma_f32_16x16x32_bf16 v[122:125], v[158:161], v[204:207], v[122:125]
	v_mfma_f32_16x16x32_bf16 v[118:121], v[144:147], v[212:215], v[118:121]
	v_mfma_f32_16x16x32_bf16 v[114:117], v[158:161], v[212:215], v[114:117]
	v_mfma_f32_16x16x32_bf16 v[110:113], v[144:147], v[220:223], v[110:113]
	v_mfma_f32_16x16x32_bf16 v[106:109], v[158:161], v[220:223], v[106:109]
	v_mfma_f32_16x16x32_bf16 v[102:105], v[144:147], v[228:231], v[102:105]
	v_mfma_f32_16x16x32_bf16 v[98:101], v[158:161], v[228:231], v[98:101]
	s_setprio 0
	s_setprio 1
	v_mfma_f32_16x16x32_bf16 v[62:65], v[162:165], v[200:203], v[62:65]
	v_mfma_f32_16x16x32_bf16 v[58:61], v[174:177], v[200:203], v[58:61]
	v_mfma_f32_16x16x32_bf16 v[54:57], v[162:165], v[208:211], v[54:57]
	v_mfma_f32_16x16x32_bf16 v[50:53], v[174:177], v[208:211], v[50:53]
	v_mfma_f32_16x16x32_bf16 v[46:49], v[162:165], v[216:219], v[46:49]
	v_mfma_f32_16x16x32_bf16 v[42:45], v[174:177], v[216:219], v[42:45]
	v_mfma_f32_16x16x32_bf16 v[38:41], v[162:165], v[224:227], v[38:41]
	v_mfma_f32_16x16x32_bf16 v[34:37], v[174:177], v[224:227], v[34:37]
	v_mfma_f32_16x16x32_bf16 v[62:65], v[170:173], v[204:207], v[62:65]
	v_mfma_f32_16x16x32_bf16 v[58:61], v[178:181], v[204:207], v[58:61]
	v_mfma_f32_16x16x32_bf16 v[54:57], v[170:173], v[212:215], v[54:57]
	v_mfma_f32_16x16x32_bf16 v[50:53], v[178:181], v[212:215], v[50:53]
	v_mfma_f32_16x16x32_bf16 v[46:49], v[170:173], v[220:223], v[46:49]
	v_mfma_f32_16x16x32_bf16 v[42:45], v[178:181], v[220:223], v[42:45]
	v_mfma_f32_16x16x32_bf16 v[38:41], v[170:173], v[228:231], v[38:41]
	v_mfma_f32_16x16x32_bf16 v[34:37], v[178:181], v[228:231], v[34:37]
	s_setprio 0
	s_barrier
; #define PG8_STAGE(bufoff, gbase, voff) do { _Pragma("unroll") for (int _i = 0; _i < 2; ++_i) \
;         __builtin_amdgcn_global_load_lds((const unsigned*)((const char*)(gbase) + (voff)[_i]), (PG8_LAS unsigned*)(lds + (bufoff) + ldsw + _i * 8192), 16, 0, 0); } while (0)
; #define PG8_LDA(dst, b, h) do { _Pragma("unroll") for (int m = 0; m < 4; ++m) _Pragma("unroll") for (int k = 0; k < 2; ++k) dst[m][k] = *(const PG8_LAS bf16x8*)(lds + PG8_SA(b, h) + aoff + m * 2048 + k * 1024); } while (0)
; #define PG8_MMA(ai, bj, At, Bt) do { __builtin_amdgcn_s_setprio(1); _Pragma("unroll") for (int m = 0; m < 4; ++m) _Pragma("unroll") for (int n = 0; n < 2; ++n) _Pragma("unroll") for (int k = 0; k < 2; ++k) \
;         acc[ai][bj][m][n] = __builtin_amdgcn_mfma_f32_16x16x32_bf16(Bt[n][k], At[m][k], acc[ai][bj][m][n], 0, 0, 0); __builtin_amdgcn_s_setprio(0); } while (0)
; #define PG8_WAIT_V(n) asm volatile("s_waitcnt vmcnt(" #n ")" ::: "memory")
; #define PG8_WAIT_L(n) asm volatile("s_waitcnt lgkmcnt(" #n ")" ::: "memory")
; #define PG8_BAR __builtin_amdgcn_s_barrier()
; #define PG8_SCHED __builtin_amdgcn_sched_barrier(0)
; template <class Epi, class Sched, bool ALIGN_EPI = false, bool SP2 = false>
; __device__ __forceinline__ void gemm_phase(PG8_LAS unsigned char* lds, const Gemm g, const Sched& S, const Epi& E) {
;     ...
;         for (int t = 0; t < nt; t += 2) {
;             const bool last = (t == nt - 2);
;             const char* a1 = cA + (size_t)(t + 1) * kstep;
;             const char* a2 = last ? nA : cA + (size_t)(t + 2) * kstep; const char* b2 = last ? nB : cB + (size_t)(t + 2) * kstep;
;             const char* a3 = a2 + kstep; const char* b3 = b2 + kstep;
;     ...
;             PG8_LDA(At, 1, 1); PG8_STAGE(PG8_SB(1, 0), b3, voffB); PG8_STAGE(PG8_SB(1, 1), b3 + hstep, voffB); PG8_STAGE(PG8_SA(1, 0), a3, voffA);
;             PG8_WAIT_V(8); PG8_WAIT_L(0); PG8_BAR; PG8_MMA(1, 0, At, B0); PG8_MMA(1, 1, At, B1); PG8_BAR; PG8_SCHED;
	s_add_i32 s20, s50, s24
	v_lshl_add_u64 v[148:149], v[148:149], 0, s[38:39]
	s_mov_b32 m0, s20
	ds_read_b128 v[200:203], v169 offset:49152
	ds_read_b128 v[204:207], v169 offset:50176
	ds_read_b128 v[208:211], v169 offset:51200
	ds_read_b128 v[212:215], v169 offset:52224
	ds_read_b128 v[216:219], v169 offset:53248
	ds_read_b128 v[220:223], v169 offset:54272
	ds_read_b128 v[224:227], v169 offset:55296
	ds_read_b128 v[228:231], v169 offset:56320
	global_load_lds_dwordx4 v[148:149], off
	s_add_i32 m0, s20, 0x2000
	s_add_u32 s18, s18, 0x40080
	v_lshl_add_u64 v[148:149], v[232:233], 0, s[38:39]
	s_addc_u32 s19, s19, 0
	s_add_i32 s20, s51, s24
	global_load_lds_dwordx4 v[148:149], off
	v_lshl_add_u64 v[148:149], s[18:19], 0, v[0:1]
	s_mov_b32 m0, s20
	s_nop 0
	global_load_lds_dwordx4 v[148:149], off
	v_lshl_add_u64 v[148:149], s[18:19], 0, v[130:131]
	s_add_i32 m0, s20, 0x2000
	s_nop 0
	global_load_lds_dwordx4 v[148:149], off
	v_lshl_add_u64 v[148:149], v[234:235], 0, s[38:39]
	s_mov_b32 m0, s31
	s_nop 0
	global_load_lds_dwordx4 v[148:149], off
	v_lshl_add_u64 v[148:149], v[236:237], 0, s[38:39]
	s_mov_b32 m0, s33
	s_nop 0
	global_load_lds_dwordx4 v[148:149], off
	s_waitcnt vmcnt(8)
	s_waitcnt lgkmcnt(0)
	s_barrier
	s_setprio 1
	s_waitcnt lgkmcnt(0)
	v_mfma_f32_16x16x32_bf16 v[94:97], v[140:143], v[200:203], v[94:97]
	v_mfma_f32_16x16x32_bf16 v[90:93], v[154:157], v[200:203], v[90:93]
	v_mfma_f32_16x16x32_bf16 v[86:89], v[140:143], v[208:211], v[86:89]
	v_mfma_f32_16x16x32_bf16 v[82:85], v[154:157], v[208:211], v[82:85]
	v_mfma_f32_16x16x32_bf16 v[78:81], v[140:143], v[216:219], v[78:81]
	v_mfma_f32_16x16x32_bf16 v[74:77], v[154:157], v[216:219], v[74:77]
	v_mfma_f32_16x16x32_bf16 v[70:73], v[140:143], v[224:227], v[70:73]
	v_mfma_f32_16x16x32_bf16 v[66:69], v[154:157], v[224:227], v[66:69]
	v_mfma_f32_16x16x32_bf16 v[94:97], v[144:147], v[204:207], v[94:97]
	v_mfma_f32_16x16x32_bf16 v[90:93], v[158:161], v[204:207], v[90:93]
	v_mfma_f32_16x16x32_bf16 v[86:89], v[144:147], v[212:215], v[86:89]
	v_mfma_f32_16x16x32_bf16 v[82:85], v[158:161], v[212:215], v[82:85]
	v_mfma_f32_16x16x32_bf16 v[78:81], v[144:147], v[220:223], v[78:81]
	v_mfma_f32_16x16x32_bf16 v[74:77], v[158:161], v[220:223], v[74:77]
	v_mfma_f32_16x16x32_bf16 v[70:73], v[144:147], v[228:231], v[70:73]
	v_mfma_f32_16x16x32_bf16 v[66:69], v[158:161], v[228:231], v[66:69]
	s_setprio 0
	s_setprio 1
	v_mfma_f32_16x16x32_bf16 v[30:33], v[162:165], v[200:203], v[30:33]
	v_mfma_f32_16x16x32_bf16 v[26:29], v[174:177], v[200:203], v[26:29]
	v_mfma_f32_16x16x32_bf16 v[22:25], v[162:165], v[208:211], v[22:25]
	v_mfma_f32_16x16x32_bf16 v[18:21], v[174:177], v[208:211], v[18:21]
	v_mfma_f32_16x16x32_bf16 v[14:17], v[162:165], v[216:219], v[14:17]
	v_mfma_f32_16x16x32_bf16 v[10:13], v[174:177], v[216:219], v[10:13]
	v_mfma_f32_16x16x32_bf16 v[6:9], v[162:165], v[224:227], v[6:9]
	v_mfma_f32_16x16x32_bf16 v[2:5], v[174:177], v[224:227], v[2:5]
	v_mfma_f32_16x16x32_bf16 v[30:33], v[170:173], v[204:207], v[30:33]
	v_mfma_f32_16x16x32_bf16 v[26:29], v[178:181], v[204:207], v[26:29]
	v_mfma_f32_16x16x32_bf16 v[22:25], v[170:173], v[212:215], v[22:25]
	v_mfma_f32_16x16x32_bf16 v[18:21], v[178:181], v[212:215], v[18:21]
	v_mfma_f32_16x16x32_bf16 v[14:17], v[170:173], v[220:223], v[14:17]
	v_mfma_f32_16x16x32_bf16 v[10:13], v[178:181], v[220:223], v[10:13]
	v_mfma_f32_16x16x32_bf16 v[6:9], v[170:173], v[228:231], v[6:9]
	v_mfma_f32_16x16x32_bf16 v[2:5], v[178:181], v[228:231], v[2:5]
	s_setprio 0
	s_barrier
	s_add_i32 s49, s49, 2
	s_add_u32 s16, s16, 0x100
	s_addc_u32 s17, s17, 0
	s_add_u32 s47, s47, 0x100
	s_addc_u32 s48, s48, 0
